# strategy 9 poll-edge edit: s_sleep 1 instead of 2 in the cmpsel wait-for-compress spin
# baseline (speedup 1.0000x reference)
; #define TIDX opaque_tid()
; __device__ __forceinline__ unsigned xb_ld(unsigned* p)              { return __hip_atomic_load(p, __ATOMIC_RELAXED, __HIP_MEMORY_SCOPE_AGENT); }
; __device__ __forceinline__ void cmpsel_item(const Args& a, int it, unsigned char* lds, unsigned* cmp_done) {
;     ...
;     if (TIDX == 0) { unsigned sp = 0; while (xb_ld(cmp_done) < 128u && sp < (1u << 22)) { __builtin_amdgcn_s_sleep(2); ++sp; } }
.LBB0_248:
	s_sleep 1
	global_load_dword v0, v215, s[18:19] offset:256 sc1
	s_add_i32 s15, s14, 1
	s_cmp_lt_u32 s14, 0x3fffff
	s_cselect_b64 s[22:23], -1, 0
	s_mov_b32 s14, s15
	s_waitcnt vmcnt(0)
	v_cmp_gt_u32_e32 vcc, s65, v0
	s_and_b64 s[22:23], vcc, s[22:23]
	s_and_b64 vcc, exec, s[22:23]
	s_cbranch_vccnz .LBB0_248
